# peel first K iteration of all four GEMM K-loops: first-touch MFMAs take C=0, 64 v_mov_b64 zeroing per unit removed
# speedup vs baseline: 1.0078x; 1.0078x over previous
.LBB0_60:
	s_ashr_i32 s21, s20, 31
	s_lshl_b64 s[4:5], s[20:21], 19
	s_add_u32 s24, s66, s4
	s_addc_u32 s25, s67, s5
	s_and_b64 s[4:5], s[22:23], exec
	s_cselect_b32 s21, s25, s1
	s_cselect_b32 s27, s24, s0
	s_lshl_b32 s29, s52, 8
	s_or_b32 s30, s29, 0x80
	s_add_u32 s31, s0, 0x100
	s_addc_u32 s53, s1, 0
	s_mov_b32 s54, -2
	s_mov_b64 s[0:1], 0
	ds_read_b128 v[144:147], v178
	ds_read_b128 v[148:151], v178 offset:1024
	ds_read_b128 v[152:155], v178 offset:2048
	ds_read_b128 v[156:159], v178 offset:3072
	ds_read_b128 v[128:131], v179
	ds_read_b128 v[132:135], v179 offset:1024
	ds_read_b128 v[136:139], v179 offset:2048
	ds_read_b128 v[140:143], v179 offset:3072
	s_cmp_eq_u32 s54, 12
	s_cselect_b64 s[6:7], -1, 0
	s_add_u32 s4, s47, s0
	s_addc_u32 s5, s48, s1
	s_mov_b32 m0, s49
	ds_read_b128 v[190:193], v180
	ds_read_b128 v[194:197], v180 offset:1024
	ds_read_b128 v[198:201], v180 offset:2048
	ds_read_b128 v[202:205], v180 offset:3072
	ds_read_b128 v[206:209], v180 offset:4096
	ds_read_b128 v[210:213], v180 offset:5120
	ds_read_b128 v[214:217], v180 offset:6144
	ds_read_b128 v[218:221], v180 offset:7168
	global_load_lds_dwordx4 v168, s[4:5]
	s_mov_b32 m0, s50
	s_nop 0
	global_load_lds_dwordx4 v170, s[4:5]
	s_waitcnt vmcnt(8)
	s_waitcnt lgkmcnt(0)
	s_barrier
	s_setprio 1
	s_waitcnt lgkmcnt(0)
	v_mfma_f32_16x16x32_bf16 v[124:127], v[144:147], v[190:193], 0
	v_mfma_f32_16x16x32_bf16 v[120:123], v[152:155], v[190:193], 0
	v_mfma_f32_16x16x32_bf16 v[108:111], v[144:147], v[198:201], 0
	v_mfma_f32_16x16x32_bf16 v[104:107], v[152:155], v[198:201], 0
	v_mfma_f32_16x16x32_bf16 v[92:95], v[144:147], v[206:209], 0
	v_mfma_f32_16x16x32_bf16 v[88:91], v[152:155], v[206:209], 0
	v_mfma_f32_16x16x32_bf16 v[76:79], v[144:147], v[214:217], 0
	v_mfma_f32_16x16x32_bf16 v[72:75], v[152:155], v[214:217], 0
	v_mfma_f32_16x16x32_bf16 v[124:127], v[148:151], v[194:197], v[124:127]
	v_mfma_f32_16x16x32_bf16 v[120:123], v[156:159], v[194:197], v[120:123]
	v_mfma_f32_16x16x32_bf16 v[108:111], v[148:151], v[202:205], v[108:111]
	v_mfma_f32_16x16x32_bf16 v[104:107], v[156:159], v[202:205], v[104:107]
	v_mfma_f32_16x16x32_bf16 v[92:95], v[148:151], v[210:213], v[92:95]
	v_mfma_f32_16x16x32_bf16 v[88:91], v[156:159], v[210:213], v[88:91]
	v_mfma_f32_16x16x32_bf16 v[76:79], v[148:151], v[218:221], v[76:79]
	v_mfma_f32_16x16x32_bf16 v[72:75], v[156:159], v[218:221], v[72:75]
	v_mfma_f32_16x16x32_bf16 v[116:119], v[128:131], v[190:193], 0
	v_mfma_f32_16x16x32_bf16 v[112:115], v[136:139], v[190:193], 0
	v_mfma_f32_16x16x32_bf16 v[100:103], v[128:131], v[198:201], 0
	v_mfma_f32_16x16x32_bf16 v[96:99], v[136:139], v[198:201], 0
	v_mfma_f32_16x16x32_bf16 v[84:87], v[128:131], v[206:209], 0
	v_mfma_f32_16x16x32_bf16 v[80:83], v[136:139], v[206:209], 0
	v_mfma_f32_16x16x32_bf16 v[68:71], v[128:131], v[214:217], 0
	v_mfma_f32_16x16x32_bf16 v[64:67], v[136:139], v[214:217], 0
	v_mfma_f32_16x16x32_bf16 v[116:119], v[132:135], v[194:197], v[116:119]
	v_mfma_f32_16x16x32_bf16 v[112:115], v[140:143], v[194:197], v[112:115]
	v_mfma_f32_16x16x32_bf16 v[100:103], v[132:135], v[202:205], v[100:103]
	v_mfma_f32_16x16x32_bf16 v[96:99], v[140:143], v[202:205], v[96:99]
	v_mfma_f32_16x16x32_bf16 v[84:87], v[132:135], v[210:213], v[84:87]
	v_mfma_f32_16x16x32_bf16 v[80:83], v[140:143], v[210:213], v[80:83]
	v_mfma_f32_16x16x32_bf16 v[68:71], v[132:135], v[218:221], v[68:71]
	v_mfma_f32_16x16x32_bf16 v[64:67], v[140:143], v[218:221], v[64:67]
	s_setprio 0
	s_barrier
	s_and_b64 s[4:5], s[22:23], s[6:7]
	s_andn2_b64 vcc, exec, s[4:5]
	s_cbranch_vccnz .Lpk0_LBB0_63
	s_lshl_b32 s57, s29, 11
	s_lshl_b32 s58, s30, 11
	v_add_u32_e32 v164, s57, v247
	v_add_u32_e32 v168, s58, v247
	v_add_u32_e32 v166, 0x20000, v164
	v_add_u32_e32 v170, 0x20000, v168
	v_mov_b32_e32 v171, v165
	v_mov_b32_e32 v172, v168
	v_mov_b32_e32 v173, v165
	s_branch .Lpk0_LBB0_64

.Lpk0_LBB0_64:
	s_add_u32 s4, s0, 0x100
	s_addc_u32 s5, s1, 0
	s_and_b64 s[56:57], s[6:7], exec
	s_cselect_b32 s8, 0, s4
	s_add_u32 s55, s31, s0
	s_addc_u32 s56, s53, s1
	s_and_b64 s[0:1], s[6:7], exec
	s_cselect_b32 s1, s21, s56
	s_cselect_b32 s0, s27, s55
	s_mov_b32 m0, s35
	v_lshl_add_u64 v[222:223], s[0:1], 0, v[160:161]
	s_add_u32 s6, s0, 0x40000
	ds_read_b128 v[190:193], v180 offset:16384
	ds_read_b128 v[194:197], v180 offset:17408
	ds_read_b128 v[198:201], v180 offset:18432
	ds_read_b128 v[202:205], v180 offset:19456
	ds_read_b128 v[206:209], v180 offset:20480
	ds_read_b128 v[210:213], v180 offset:21504
	ds_read_b128 v[214:217], v180 offset:22528
	ds_read_b128 v[218:221], v180 offset:23552
	global_load_lds_dwordx4 v[222:223], off
	v_lshl_add_u64 v[224:225], s[0:1], 0, v[162:163]
	s_mov_b32 m0, s36
	s_addc_u32 s7, s1, 0
	global_load_lds_dwordx4 v[224:225], off
	v_lshl_add_u64 v[226:227], s[6:7], 0, v[160:161]
	s_mov_b32 m0, s37
	v_mov_b32_e32 v167, v165
	global_load_lds_dwordx4 v[226:227], off
	v_lshl_add_u64 v[226:227], s[6:7], 0, v[162:163]
	s_mov_b32 m0, s38
	v_lshl_add_u64 v[228:229], s[2:3], 0, v[166:167]
	global_load_lds_dwordx4 v[226:227], off
	v_lshl_add_u64 v[226:227], s[2:3], 0, v[164:165]
	v_lshl_add_u64 v[226:227], v[226:227], 0, s[8:9]
	s_mov_b32 m0, s34
	v_lshl_add_u64 v[228:229], v[228:229], 0, s[8:9]
	global_load_lds_dwordx4 v[226:227], off
	s_mov_b32 m0, s39
	s_nop 0
	global_load_lds_dwordx4 v[228:229], off
	s_waitcnt vmcnt(8)
	s_waitcnt lgkmcnt(0)
	s_barrier
	s_setprio 1
	s_waitcnt lgkmcnt(0)
	v_mfma_f32_16x16x32_bf16 v[60:63], v[144:147], v[190:193], 0
	v_mfma_f32_16x16x32_bf16 v[56:59], v[152:155], v[190:193], 0
	v_mfma_f32_16x16x32_bf16 v[44:47], v[144:147], v[198:201], 0
	v_mfma_f32_16x16x32_bf16 v[40:43], v[152:155], v[198:201], 0
	v_mfma_f32_16x16x32_bf16 v[28:31], v[144:147], v[206:209], 0
	v_mfma_f32_16x16x32_bf16 v[24:27], v[152:155], v[206:209], 0
	v_mfma_f32_16x16x32_bf16 v[12:15], v[144:147], v[214:217], 0
	v_mfma_f32_16x16x32_bf16 v[8:11], v[152:155], v[214:217], 0
	v_mfma_f32_16x16x32_bf16 v[60:63], v[148:151], v[194:197], v[60:63]
	v_mfma_f32_16x16x32_bf16 v[56:59], v[156:159], v[194:197], v[56:59]
	v_mfma_f32_16x16x32_bf16 v[44:47], v[148:151], v[202:205], v[44:47]
	v_mfma_f32_16x16x32_bf16 v[40:43], v[156:159], v[202:205], v[40:43]
	v_mfma_f32_16x16x32_bf16 v[28:31], v[148:151], v[210:213], v[28:31]
	v_mfma_f32_16x16x32_bf16 v[24:27], v[156:159], v[210:213], v[24:27]
	v_mfma_f32_16x16x32_bf16 v[12:15], v[148:151], v[218:221], v[12:15]
	v_mfma_f32_16x16x32_bf16 v[8:11], v[156:159], v[218:221], v[8:11]
	v_mfma_f32_16x16x32_bf16 v[52:55], v[128:131], v[190:193], 0
	v_mfma_f32_16x16x32_bf16 v[48:51], v[136:139], v[190:193], 0
	v_mfma_f32_16x16x32_bf16 v[36:39], v[128:131], v[198:201], 0
	v_mfma_f32_16x16x32_bf16 v[32:35], v[136:139], v[198:201], 0
	v_mfma_f32_16x16x32_bf16 v[20:23], v[128:131], v[206:209], 0
	v_mfma_f32_16x16x32_bf16 v[16:19], v[136:139], v[206:209], 0
	v_mfma_f32_16x16x32_bf16 v[4:7], v[128:131], v[214:217], 0
	v_mfma_f32_16x16x32_bf16 v[0:3], v[136:139], v[214:217], 0
	v_mfma_f32_16x16x32_bf16 v[52:55], v[132:135], v[194:197], v[52:55]
	v_mfma_f32_16x16x32_bf16 v[48:51], v[140:143], v[194:197], v[48:51]
	v_mfma_f32_16x16x32_bf16 v[36:39], v[132:135], v[202:205], v[36:39]
	v_mfma_f32_16x16x32_bf16 v[32:35], v[140:143], v[202:205], v[32:35]
	v_mfma_f32_16x16x32_bf16 v[20:23], v[132:135], v[210:213], v[20:23]
	v_mfma_f32_16x16x32_bf16 v[16:19], v[140:143], v[210:213], v[16:19]
	v_mfma_f32_16x16x32_bf16 v[4:7], v[132:135], v[218:221], v[4:7]
	v_mfma_f32_16x16x32_bf16 v[0:3], v[140:143], v[218:221], v[0:3]
	s_setprio 0
	s_barrier
	s_add_i32 s6, 0, 0x18000
	s_add_i32 s7, 0, 0x1c000
	v_add_u32_e32 v140, s6, v176
	v_add_u32_e32 v156, s7, v176
	ds_read_b128 v[128:131], v140
	ds_read_b128 v[132:135], v140 offset:1024
	ds_read_b128 v[136:139], v140 offset:2048
	ds_read_b128 v[140:143], v140 offset:3072
	ds_read_b128 v[144:147], v156
	ds_read_b128 v[148:151], v156 offset:1024
	ds_read_b128 v[152:155], v156 offset:2048
	ds_read_b128 v[156:159], v156 offset:3072
	v_lshl_add_u64 v[172:173], s[2:3], 0, v[172:173]
	s_mov_b32 m0, s40
	v_lshl_add_u64 v[172:173], v[172:173], 0, s[8:9]
	ds_read_b128 v[190:193], v180 offset:32768
	ds_read_b128 v[194:197], v180 offset:33792
	ds_read_b128 v[198:201], v180 offset:34816
	ds_read_b128 v[202:205], v180 offset:35840
	ds_read_b128 v[206:209], v180 offset:36864
	ds_read_b128 v[210:213], v180 offset:37888
	ds_read_b128 v[214:217], v180 offset:38912
	ds_read_b128 v[218:221], v180 offset:39936
	global_load_lds_dwordx4 v[172:173], off
	v_lshl_add_u64 v[172:173], s[2:3], 0, v[170:171]
	v_lshl_add_u64 v[172:173], v[172:173], 0, s[8:9]
	s_mov_b32 m0, s41
	s_nop 0
	global_load_lds_dwordx4 v[172:173], off
	s_waitcnt vmcnt(8)
	s_waitcnt lgkmcnt(0)
	s_barrier
	s_setprio 1
	s_waitcnt lgkmcnt(0)
	v_mfma_f32_16x16x32_bf16 v[124:127], v[128:131], v[190:193], v[124:127]
	v_mfma_f32_16x16x32_bf16 v[120:123], v[136:139], v[190:193], v[120:123]
	v_mfma_f32_16x16x32_bf16 v[108:111], v[128:131], v[198:201], v[108:111]
	v_mfma_f32_16x16x32_bf16 v[104:107], v[136:139], v[198:201], v[104:107]
	v_mfma_f32_16x16x32_bf16 v[92:95], v[128:131], v[206:209], v[92:95]
	v_mfma_f32_16x16x32_bf16 v[88:91], v[136:139], v[206:209], v[88:91]
	v_mfma_f32_16x16x32_bf16 v[76:79], v[128:131], v[214:217], v[76:79]
	v_mfma_f32_16x16x32_bf16 v[72:75], v[136:139], v[214:217], v[72:75]
	v_mfma_f32_16x16x32_bf16 v[124:127], v[132:135], v[194:197], v[124:127]
	v_mfma_f32_16x16x32_bf16 v[120:123], v[140:143], v[194:197], v[120:123]
	v_mfma_f32_16x16x32_bf16 v[108:111], v[132:135], v[202:205], v[108:111]
	v_mfma_f32_16x16x32_bf16 v[104:107], v[140:143], v[202:205], v[104:107]
	v_mfma_f32_16x16x32_bf16 v[92:95], v[132:135], v[210:213], v[92:95]
	v_mfma_f32_16x16x32_bf16 v[88:91], v[140:143], v[210:213], v[88:91]
	v_mfma_f32_16x16x32_bf16 v[76:79], v[132:135], v[218:221], v[76:79]
	v_mfma_f32_16x16x32_bf16 v[72:75], v[140:143], v[218:221], v[72:75]
	v_mfma_f32_16x16x32_bf16 v[116:119], v[144:147], v[190:193], v[116:119]
	v_mfma_f32_16x16x32_bf16 v[112:115], v[152:155], v[190:193], v[112:115]
	v_mfma_f32_16x16x32_bf16 v[100:103], v[144:147], v[198:201], v[100:103]
	v_mfma_f32_16x16x32_bf16 v[96:99], v[152:155], v[198:201], v[96:99]
	v_mfma_f32_16x16x32_bf16 v[84:87], v[144:147], v[206:209], v[84:87]
	v_mfma_f32_16x16x32_bf16 v[80:83], v[152:155], v[206:209], v[80:83]
	v_mfma_f32_16x16x32_bf16 v[68:71], v[144:147], v[214:217], v[68:71]
	v_mfma_f32_16x16x32_bf16 v[64:67], v[152:155], v[214:217], v[64:67]
	v_mfma_f32_16x16x32_bf16 v[116:119], v[148:151], v[194:197], v[116:119]
	v_mfma_f32_16x16x32_bf16 v[112:115], v[156:159], v[194:197], v[112:115]
	v_mfma_f32_16x16x32_bf16 v[100:103], v[148:151], v[202:205], v[100:103]
	v_mfma_f32_16x16x32_bf16 v[96:99], v[156:159], v[202:205], v[96:99]
	v_mfma_f32_16x16x32_bf16 v[84:87], v[148:151], v[210:213], v[84:87]
	v_mfma_f32_16x16x32_bf16 v[80:83], v[156:159], v[210:213], v[80:83]
	v_mfma_f32_16x16x32_bf16 v[68:71], v[148:151], v[218:221], v[68:71]
	v_mfma_f32_16x16x32_bf16 v[64:67], v[156:159], v[218:221], v[64:67]
	s_setprio 0
	s_barrier
	s_add_i32 s6, s6, s84
	v_lshl_add_u64 v[172:173], v[222:223], 0, s[14:15]
	s_mov_b32 m0, s6
	ds_read_b128 v[190:193], v180 offset:49152
	ds_read_b128 v[194:197], v180 offset:50176
	ds_read_b128 v[198:201], v180 offset:51200
	ds_read_b128 v[202:205], v180 offset:52224
	ds_read_b128 v[206:209], v180 offset:53248
	ds_read_b128 v[210:213], v180 offset:54272
	ds_read_b128 v[214:217], v180 offset:55296
	ds_read_b128 v[218:221], v180 offset:56320
	global_load_lds_dwordx4 v[172:173], off
	s_add_i32 m0, s6, 0x2000
	s_add_u32 s0, s0, 0x40080
	v_lshl_add_u64 v[172:173], v[224:225], 0, s[14:15]
	s_addc_u32 s1, s1, 0
	s_add_i32 s6, s7, s84
	global_load_lds_dwordx4 v[172:173], off
	v_lshl_add_u64 v[172:173], s[0:1], 0, v[160:161]
	s_mov_b32 m0, s6
	s_nop 0
	global_load_lds_dwordx4 v[172:173], off
	v_lshl_add_u64 v[172:173], s[0:1], 0, v[162:163]
	s_add_i32 m0, s6, 0x2000
	s_nop 0
	global_load_lds_dwordx4 v[172:173], off
	v_lshl_add_u64 v[172:173], v[226:227], 0, s[14:15]
	s_mov_b32 m0, s42
	s_nop 0
	global_load_lds_dwordx4 v[172:173], off
	v_lshl_add_u64 v[172:173], v[228:229], 0, s[14:15]
	s_mov_b32 m0, s43
	s_nop 0
	global_load_lds_dwordx4 v[172:173], off
	s_waitcnt vmcnt(8)
	s_waitcnt lgkmcnt(0)
	s_barrier
	s_setprio 1
	s_waitcnt lgkmcnt(0)
	v_mfma_f32_16x16x32_bf16 v[60:63], v[128:131], v[190:193], v[60:63]
	v_mfma_f32_16x16x32_bf16 v[56:59], v[136:139], v[190:193], v[56:59]
	v_mfma_f32_16x16x32_bf16 v[44:47], v[128:131], v[198:201], v[44:47]
	v_mfma_f32_16x16x32_bf16 v[40:43], v[136:139], v[198:201], v[40:43]
	v_mfma_f32_16x16x32_bf16 v[28:31], v[128:131], v[206:209], v[28:31]
	v_mfma_f32_16x16x32_bf16 v[24:27], v[136:139], v[206:209], v[24:27]
	v_mfma_f32_16x16x32_bf16 v[12:15], v[128:131], v[214:217], v[12:15]
	v_mfma_f32_16x16x32_bf16 v[8:11], v[136:139], v[214:217], v[8:11]
	v_mfma_f32_16x16x32_bf16 v[60:63], v[132:135], v[194:197], v[60:63]
	v_mfma_f32_16x16x32_bf16 v[56:59], v[140:143], v[194:197], v[56:59]
	v_mfma_f32_16x16x32_bf16 v[44:47], v[132:135], v[202:205], v[44:47]
	v_mfma_f32_16x16x32_bf16 v[40:43], v[140:143], v[202:205], v[40:43]
	v_mfma_f32_16x16x32_bf16 v[28:31], v[132:135], v[210:213], v[28:31]
	v_mfma_f32_16x16x32_bf16 v[24:27], v[140:143], v[210:213], v[24:27]
	v_mfma_f32_16x16x32_bf16 v[12:15], v[132:135], v[218:221], v[12:15]
	v_mfma_f32_16x16x32_bf16 v[8:11], v[140:143], v[218:221], v[8:11]
	v_mfma_f32_16x16x32_bf16 v[52:55], v[144:147], v[190:193], v[52:55]
	v_mfma_f32_16x16x32_bf16 v[48:51], v[152:155], v[190:193], v[48:51]
	v_mfma_f32_16x16x32_bf16 v[36:39], v[144:147], v[198:201], v[36:39]
	v_mfma_f32_16x16x32_bf16 v[32:35], v[152:155], v[198:201], v[32:35]
	v_mfma_f32_16x16x32_bf16 v[20:23], v[144:147], v[206:209], v[20:23]
	v_mfma_f32_16x16x32_bf16 v[16:19], v[152:155], v[206:209], v[16:19]
	v_mfma_f32_16x16x32_bf16 v[4:7], v[144:147], v[214:217], v[4:7]
	v_mfma_f32_16x16x32_bf16 v[0:3], v[152:155], v[214:217], v[0:3]
	v_mfma_f32_16x16x32_bf16 v[52:55], v[148:151], v[194:197], v[52:55]
	v_mfma_f32_16x16x32_bf16 v[48:51], v[156:159], v[194:197], v[48:51]
	v_mfma_f32_16x16x32_bf16 v[36:39], v[148:151], v[202:205], v[36:39]
	v_mfma_f32_16x16x32_bf16 v[32:35], v[156:159], v[202:205], v[32:35]
	v_mfma_f32_16x16x32_bf16 v[20:23], v[148:151], v[210:213], v[20:23]
	v_mfma_f32_16x16x32_bf16 v[16:19], v[156:159], v[210:213], v[16:19]
	v_mfma_f32_16x16x32_bf16 v[4:7], v[148:151], v[218:221], v[4:7]
	v_mfma_f32_16x16x32_bf16 v[0:3], v[156:159], v[218:221], v[0:3]
	s_setprio 0
	s_barrier
	s_add_i32 s54, s54, 2
	s_cmp_gt_u32 s54, 13
	s_cbranch_scc1 .LBB0_66
	s_mov_b64 s[0:1], s[4:5]
	s_branch .LBB0_61

.LBB0_720:
	s_ashr_i32 s15, s14, 31
	s_lshl_b64 s[18:19], s[14:15], 19
	s_add_u32 s18, s13, s18
	s_addc_u32 s19, s26, s19
	s_and_b64 s[22:23], s[16:17], exec
	s_cselect_b32 s15, s19, s21
	s_cselect_b32 s46, s18, s20
	s_lshl_b32 s47, s43, 8
	s_or_b32 s48, s47, 0x80
	s_add_u32 s49, s20, 0x100
	s_addc_u32 s50, s21, 0
	s_mov_b32 s51, -2
	s_mov_b64 s[20:21], 0
	s_waitcnt vmcnt(0)
	ds_read_b128 v[144:147], v177
	ds_read_b128 v[148:151], v177 offset:1024
	ds_read_b128 v[152:155], v177 offset:2048
	ds_read_b128 v[156:159], v177 offset:3072
	ds_read_b128 v[128:131], v178
	ds_read_b128 v[132:135], v178 offset:1024
	ds_read_b128 v[136:139], v178 offset:2048
	ds_read_b128 v[140:143], v178 offset:3072
	s_cmp_eq_u32 s51, 12
	s_cselect_b64 s[24:25], -1, 0
	s_add_i32 m0, s27, 0xc000
	s_add_u32 s22, s40, s20
	s_addc_u32 s23, s41, s21
	ds_read_b128 v[180:183], v179
	ds_read_b128 v[184:187], v179 offset:1024
	ds_read_b128 v[188:191], v179 offset:2048
	ds_read_b128 v[192:195], v179 offset:3072
	ds_read_b128 v[196:199], v179 offset:4096
	ds_read_b128 v[200:203], v179 offset:5120
	ds_read_b128 v[204:207], v179 offset:6144
	ds_read_b128 v[208:211], v179 offset:7168
	global_load_lds_dwordx4 v168, s[22:23]
	s_add_i32 m0, s27, 0xe000
	s_nop 0
	global_load_lds_dwordx4 v170, s[22:23]
	s_waitcnt vmcnt(8)
	s_waitcnt lgkmcnt(0)
	s_barrier
	s_setprio 1
	s_waitcnt lgkmcnt(0)
	v_mfma_f32_16x16x32_bf16 v[124:127], v[144:147], v[180:183], 0
	v_mfma_f32_16x16x32_bf16 v[120:123], v[152:155], v[180:183], 0
	v_mfma_f32_16x16x32_bf16 v[112:115], v[144:147], v[188:191], 0
	v_mfma_f32_16x16x32_bf16 v[104:107], v[152:155], v[188:191], 0
	v_mfma_f32_16x16x32_bf16 v[96:99], v[144:147], v[196:199], 0
	v_mfma_f32_16x16x32_bf16 v[88:91], v[152:155], v[196:199], 0
	v_mfma_f32_16x16x32_bf16 v[80:83], v[144:147], v[204:207], 0
	v_mfma_f32_16x16x32_bf16 v[72:75], v[152:155], v[204:207], 0
	v_mfma_f32_16x16x32_bf16 v[124:127], v[148:151], v[184:187], v[124:127]
	v_mfma_f32_16x16x32_bf16 v[120:123], v[156:159], v[184:187], v[120:123]
	v_mfma_f32_16x16x32_bf16 v[112:115], v[148:151], v[192:195], v[112:115]
	v_mfma_f32_16x16x32_bf16 v[104:107], v[156:159], v[192:195], v[104:107]
	v_mfma_f32_16x16x32_bf16 v[96:99], v[148:151], v[200:203], v[96:99]
	v_mfma_f32_16x16x32_bf16 v[88:91], v[156:159], v[200:203], v[88:91]
	v_mfma_f32_16x16x32_bf16 v[80:83], v[148:151], v[208:211], v[80:83]
	v_mfma_f32_16x16x32_bf16 v[72:75], v[156:159], v[208:211], v[72:75]
	v_mfma_f32_16x16x32_bf16 v[116:119], v[128:131], v[180:183], 0
	v_mfma_f32_16x16x32_bf16 v[108:111], v[136:139], v[180:183], 0
	v_mfma_f32_16x16x32_bf16 v[100:103], v[128:131], v[188:191], 0
	v_mfma_f32_16x16x32_bf16 v[92:95], v[136:139], v[188:191], 0
	v_mfma_f32_16x16x32_bf16 v[84:87], v[128:131], v[196:199], 0
	v_mfma_f32_16x16x32_bf16 v[76:79], v[136:139], v[196:199], 0
	v_mfma_f32_16x16x32_bf16 v[68:71], v[128:131], v[204:207], 0
	v_mfma_f32_16x16x32_bf16 v[64:67], v[136:139], v[204:207], 0
	v_mfma_f32_16x16x32_bf16 v[116:119], v[132:135], v[184:187], v[116:119]
	v_mfma_f32_16x16x32_bf16 v[108:111], v[140:143], v[184:187], v[108:111]
	v_mfma_f32_16x16x32_bf16 v[100:103], v[132:135], v[192:195], v[100:103]
	v_mfma_f32_16x16x32_bf16 v[92:95], v[140:143], v[192:195], v[92:95]
	v_mfma_f32_16x16x32_bf16 v[84:87], v[132:135], v[200:203], v[84:87]
	v_mfma_f32_16x16x32_bf16 v[76:79], v[140:143], v[200:203], v[76:79]
	v_mfma_f32_16x16x32_bf16 v[68:71], v[132:135], v[208:211], v[68:71]
	v_mfma_f32_16x16x32_bf16 v[64:67], v[140:143], v[208:211], v[64:67]
	s_setprio 0
	s_barrier
	s_and_b64 s[22:23], s[16:17], s[24:25]
	s_andn2_b64 vcc, exec, s[22:23]
	s_cbranch_vccnz .Lpk1_LBB0_723
	s_lshl_b32 s57, s47, 11
	s_lshl_b32 s58, s48, 11
	v_add_u32_e32 v164, s57, v247
	v_add_u32_e32 v168, s58, v247
	v_add_u32_e32 v166, 0x20000, v164
	v_add_u32_e32 v170, 0x20000, v168
	v_mov_b32_e32 v171, v165
	v_mov_b32_e32 v172, v168
	v_mov_b32_e32 v173, v165
	s_branch .Lpk1_LBB0_724

.Lpk1_LBB0_724:
	s_add_u32 s22, s20, 0x100
	s_addc_u32 s23, s21, 0
	s_and_b64 s[52:53], s[24:25], exec
	s_cselect_b32 s0, 0, s22
	s_add_u32 s52, s49, s20
	s_addc_u32 s53, s50, s21
	s_and_b64 s[20:21], s[24:25], exec
	s_cselect_b32 s21, s15, s53
	s_cselect_b32 s20, s46, s52
	s_mov_b32 m0, s28
	v_lshl_add_u64 v[212:213], s[20:21], 0, v[162:163]
	s_add_u32 s24, s20, 0x40000
	ds_read_b128 v[180:183], v179 offset:16384
	ds_read_b128 v[184:187], v179 offset:17408
	ds_read_b128 v[188:191], v179 offset:18432
	ds_read_b128 v[192:195], v179 offset:19456
	ds_read_b128 v[196:199], v179 offset:20480
	ds_read_b128 v[200:203], v179 offset:21504
	ds_read_b128 v[204:207], v179 offset:22528
	ds_read_b128 v[208:211], v179 offset:23552
	global_load_lds_dwordx4 v[212:213], off
	v_lshl_add_u64 v[214:215], s[20:21], 0, v[160:161]
	s_mov_b32 m0, s29
	s_addc_u32 s25, s21, 0
	global_load_lds_dwordx4 v[214:215], off
	v_lshl_add_u64 v[216:217], s[24:25], 0, v[162:163]
	s_mov_b32 m0, s30
	v_mov_b32_e32 v167, v165
	global_load_lds_dwordx4 v[216:217], off
	v_lshl_add_u64 v[216:217], s[24:25], 0, v[160:161]
	s_mov_b32 m0, s31
	v_lshl_add_u64 v[218:219], s[2:3], 0, v[166:167]
	global_load_lds_dwordx4 v[216:217], off
	v_lshl_add_u64 v[216:217], s[2:3], 0, v[164:165]
	v_lshl_add_u64 v[216:217], v[216:217], 0, s[0:1]
	s_mov_b32 m0, s27
	v_lshl_add_u64 v[218:219], v[218:219], 0, s[0:1]
	global_load_lds_dwordx4 v[216:217], off
	s_mov_b32 m0, s34
	s_nop 0
	global_load_lds_dwordx4 v[218:219], off
	s_waitcnt vmcnt(8)
	s_waitcnt lgkmcnt(0)
	s_barrier
	s_setprio 1
	s_waitcnt lgkmcnt(0)
	v_mfma_f32_16x16x32_bf16 v[60:63], v[144:147], v[180:183], 0
	v_mfma_f32_16x16x32_bf16 v[56:59], v[152:155], v[180:183], 0
	v_mfma_f32_16x16x32_bf16 v[48:51], v[144:147], v[188:191], 0
	v_mfma_f32_16x16x32_bf16 v[40:43], v[152:155], v[188:191], 0
	v_mfma_f32_16x16x32_bf16 v[32:35], v[144:147], v[196:199], 0
	v_mfma_f32_16x16x32_bf16 v[24:27], v[152:155], v[196:199], 0
	v_mfma_f32_16x16x32_bf16 v[16:19], v[144:147], v[204:207], 0
	v_mfma_f32_16x16x32_bf16 v[8:11], v[152:155], v[204:207], 0
	v_mfma_f32_16x16x32_bf16 v[60:63], v[148:151], v[184:187], v[60:63]
	v_mfma_f32_16x16x32_bf16 v[56:59], v[156:159], v[184:187], v[56:59]
	v_mfma_f32_16x16x32_bf16 v[48:51], v[148:151], v[192:195], v[48:51]
	v_mfma_f32_16x16x32_bf16 v[40:43], v[156:159], v[192:195], v[40:43]
	v_mfma_f32_16x16x32_bf16 v[32:35], v[148:151], v[200:203], v[32:35]
	v_mfma_f32_16x16x32_bf16 v[24:27], v[156:159], v[200:203], v[24:27]
	v_mfma_f32_16x16x32_bf16 v[16:19], v[148:151], v[208:211], v[16:19]
	v_mfma_f32_16x16x32_bf16 v[8:11], v[156:159], v[208:211], v[8:11]
	v_mfma_f32_16x16x32_bf16 v[52:55], v[128:131], v[180:183], 0
	v_mfma_f32_16x16x32_bf16 v[44:47], v[136:139], v[180:183], 0
	v_mfma_f32_16x16x32_bf16 v[36:39], v[128:131], v[188:191], 0
	v_mfma_f32_16x16x32_bf16 v[28:31], v[136:139], v[188:191], 0
	v_mfma_f32_16x16x32_bf16 v[20:23], v[128:131], v[196:199], 0
	v_mfma_f32_16x16x32_bf16 v[12:15], v[136:139], v[196:199], 0
	v_mfma_f32_16x16x32_bf16 v[4:7], v[128:131], v[204:207], 0
	v_mfma_f32_16x16x32_bf16 v[0:3], v[136:139], v[204:207], 0
	v_mfma_f32_16x16x32_bf16 v[52:55], v[132:135], v[184:187], v[52:55]
	v_mfma_f32_16x16x32_bf16 v[44:47], v[140:143], v[184:187], v[44:47]
	v_mfma_f32_16x16x32_bf16 v[36:39], v[132:135], v[192:195], v[36:39]
	v_mfma_f32_16x16x32_bf16 v[28:31], v[140:143], v[192:195], v[28:31]
	v_mfma_f32_16x16x32_bf16 v[20:23], v[132:135], v[200:203], v[20:23]
	v_mfma_f32_16x16x32_bf16 v[12:15], v[140:143], v[200:203], v[12:15]
	v_mfma_f32_16x16x32_bf16 v[4:7], v[132:135], v[208:211], v[4:7]
	v_mfma_f32_16x16x32_bf16 v[0:3], v[140:143], v[208:211], v[0:3]
	s_setprio 0
	s_barrier
	s_add_i32 s24, 0, 0x18000
	s_add_i32 s25, 0, 0x1c000
	v_add_u32_e32 v140, s24, v176
	v_add_u32_e32 v156, s25, v176
	ds_read_b128 v[128:131], v140
	ds_read_b128 v[132:135], v140 offset:1024
	ds_read_b128 v[136:139], v140 offset:2048
	ds_read_b128 v[140:143], v140 offset:3072
	ds_read_b128 v[144:147], v156
	ds_read_b128 v[148:151], v156 offset:1024
	ds_read_b128 v[152:155], v156 offset:2048
	ds_read_b128 v[156:159], v156 offset:3072
	v_lshl_add_u64 v[172:173], s[2:3], 0, v[172:173]
	s_mov_b32 m0, s35
	v_lshl_add_u64 v[172:173], v[172:173], 0, s[0:1]
	ds_read_b128 v[180:183], v179 offset:32768
	ds_read_b128 v[184:187], v179 offset:33792
	ds_read_b128 v[188:191], v179 offset:34816
	ds_read_b128 v[192:195], v179 offset:35840
	ds_read_b128 v[196:199], v179 offset:36864
	ds_read_b128 v[200:203], v179 offset:37888
	ds_read_b128 v[204:207], v179 offset:38912
	ds_read_b128 v[208:211], v179 offset:39936
	global_load_lds_dwordx4 v[172:173], off
	v_lshl_add_u64 v[172:173], s[2:3], 0, v[170:171]
	v_lshl_add_u64 v[172:173], v[172:173], 0, s[0:1]
	s_mov_b32 m0, s36
	s_nop 0
	global_load_lds_dwordx4 v[172:173], off
	s_waitcnt vmcnt(8)
	s_waitcnt lgkmcnt(0)
	s_barrier
	s_setprio 1
	s_waitcnt lgkmcnt(0)
	v_mfma_f32_16x16x32_bf16 v[124:127], v[128:131], v[180:183], v[124:127]
	v_mfma_f32_16x16x32_bf16 v[120:123], v[136:139], v[180:183], v[120:123]
	v_mfma_f32_16x16x32_bf16 v[112:115], v[128:131], v[188:191], v[112:115]
	v_mfma_f32_16x16x32_bf16 v[104:107], v[136:139], v[188:191], v[104:107]
	v_mfma_f32_16x16x32_bf16 v[96:99], v[128:131], v[196:199], v[96:99]
	v_mfma_f32_16x16x32_bf16 v[88:91], v[136:139], v[196:199], v[88:91]
	v_mfma_f32_16x16x32_bf16 v[80:83], v[128:131], v[204:207], v[80:83]
	v_mfma_f32_16x16x32_bf16 v[72:75], v[136:139], v[204:207], v[72:75]
	v_mfma_f32_16x16x32_bf16 v[124:127], v[132:135], v[184:187], v[124:127]
	v_mfma_f32_16x16x32_bf16 v[120:123], v[140:143], v[184:187], v[120:123]
	v_mfma_f32_16x16x32_bf16 v[112:115], v[132:135], v[192:195], v[112:115]
	v_mfma_f32_16x16x32_bf16 v[104:107], v[140:143], v[192:195], v[104:107]
	v_mfma_f32_16x16x32_bf16 v[96:99], v[132:135], v[200:203], v[96:99]
	v_mfma_f32_16x16x32_bf16 v[88:91], v[140:143], v[200:203], v[88:91]
	v_mfma_f32_16x16x32_bf16 v[80:83], v[132:135], v[208:211], v[80:83]
	v_mfma_f32_16x16x32_bf16 v[72:75], v[140:143], v[208:211], v[72:75]
	v_mfma_f32_16x16x32_bf16 v[116:119], v[144:147], v[180:183], v[116:119]
	v_mfma_f32_16x16x32_bf16 v[108:111], v[152:155], v[180:183], v[108:111]
	v_mfma_f32_16x16x32_bf16 v[100:103], v[144:147], v[188:191], v[100:103]
	v_mfma_f32_16x16x32_bf16 v[92:95], v[152:155], v[188:191], v[92:95]
	v_mfma_f32_16x16x32_bf16 v[84:87], v[144:147], v[196:199], v[84:87]
	v_mfma_f32_16x16x32_bf16 v[76:79], v[152:155], v[196:199], v[76:79]
	v_mfma_f32_16x16x32_bf16 v[68:71], v[144:147], v[204:207], v[68:71]
	v_mfma_f32_16x16x32_bf16 v[64:67], v[152:155], v[204:207], v[64:67]
	v_mfma_f32_16x16x32_bf16 v[116:119], v[148:151], v[184:187], v[116:119]
	v_mfma_f32_16x16x32_bf16 v[108:111], v[156:159], v[184:187], v[108:111]
	v_mfma_f32_16x16x32_bf16 v[100:103], v[148:151], v[192:195], v[100:103]
	v_mfma_f32_16x16x32_bf16 v[92:95], v[156:159], v[192:195], v[92:95]
	v_mfma_f32_16x16x32_bf16 v[84:87], v[148:151], v[200:203], v[84:87]
	v_mfma_f32_16x16x32_bf16 v[76:79], v[156:159], v[200:203], v[76:79]
	v_mfma_f32_16x16x32_bf16 v[68:71], v[148:151], v[208:211], v[68:71]
	v_mfma_f32_16x16x32_bf16 v[64:67], v[156:159], v[208:211], v[64:67]
	s_setprio 0
	s_barrier
	s_add_i32 s0, s24, s84
	v_lshl_add_u64 v[172:173], v[212:213], 0, s[6:7]
	s_mov_b32 m0, s0
	ds_read_b128 v[180:183], v179 offset:49152
	ds_read_b128 v[184:187], v179 offset:50176
	ds_read_b128 v[188:191], v179 offset:51200
	ds_read_b128 v[192:195], v179 offset:52224
	ds_read_b128 v[196:199], v179 offset:53248
	ds_read_b128 v[200:203], v179 offset:54272
	ds_read_b128 v[204:207], v179 offset:55296
	ds_read_b128 v[208:211], v179 offset:56320
	global_load_lds_dwordx4 v[172:173], off
	s_add_i32 m0, s0, 0x2000
	s_add_u32 s20, s20, 0x40080
	v_lshl_add_u64 v[172:173], v[214:215], 0, s[6:7]
	s_addc_u32 s21, s21, 0
	s_add_i32 s0, s25, s84
	global_load_lds_dwordx4 v[172:173], off
	v_lshl_add_u64 v[172:173], s[20:21], 0, v[162:163]
	s_mov_b32 m0, s0
	s_nop 0
	global_load_lds_dwordx4 v[172:173], off
	v_lshl_add_u64 v[172:173], s[20:21], 0, v[160:161]
	s_add_i32 m0, s0, 0x2000
	s_nop 0
	global_load_lds_dwordx4 v[172:173], off
	v_lshl_add_u64 v[172:173], v[216:217], 0, s[6:7]
	s_mov_b32 m0, s37
	s_nop 0
	global_load_lds_dwordx4 v[172:173], off
	v_lshl_add_u64 v[172:173], v[218:219], 0, s[6:7]
	s_mov_b32 m0, s38
	s_nop 0
	global_load_lds_dwordx4 v[172:173], off
	s_waitcnt vmcnt(8)
	s_waitcnt lgkmcnt(0)
	s_barrier
	s_setprio 1
	s_waitcnt lgkmcnt(0)
	v_mfma_f32_16x16x32_bf16 v[60:63], v[128:131], v[180:183], v[60:63]
	v_mfma_f32_16x16x32_bf16 v[56:59], v[136:139], v[180:183], v[56:59]
	v_mfma_f32_16x16x32_bf16 v[48:51], v[128:131], v[188:191], v[48:51]
	v_mfma_f32_16x16x32_bf16 v[40:43], v[136:139], v[188:191], v[40:43]
	v_mfma_f32_16x16x32_bf16 v[32:35], v[128:131], v[196:199], v[32:35]
	v_mfma_f32_16x16x32_bf16 v[24:27], v[136:139], v[196:199], v[24:27]
	v_mfma_f32_16x16x32_bf16 v[16:19], v[128:131], v[204:207], v[16:19]
	v_mfma_f32_16x16x32_bf16 v[8:11], v[136:139], v[204:207], v[8:11]
	v_mfma_f32_16x16x32_bf16 v[60:63], v[132:135], v[184:187], v[60:63]
	v_mfma_f32_16x16x32_bf16 v[56:59], v[140:143], v[184:187], v[56:59]
	v_mfma_f32_16x16x32_bf16 v[48:51], v[132:135], v[192:195], v[48:51]
	v_mfma_f32_16x16x32_bf16 v[40:43], v[140:143], v[192:195], v[40:43]
	v_mfma_f32_16x16x32_bf16 v[32:35], v[132:135], v[200:203], v[32:35]
	v_mfma_f32_16x16x32_bf16 v[24:27], v[140:143], v[200:203], v[24:27]
	v_mfma_f32_16x16x32_bf16 v[16:19], v[132:135], v[208:211], v[16:19]
	v_mfma_f32_16x16x32_bf16 v[8:11], v[140:143], v[208:211], v[8:11]
	v_mfma_f32_16x16x32_bf16 v[52:55], v[144:147], v[180:183], v[52:55]
	v_mfma_f32_16x16x32_bf16 v[44:47], v[152:155], v[180:183], v[44:47]
	v_mfma_f32_16x16x32_bf16 v[36:39], v[144:147], v[188:191], v[36:39]
	v_mfma_f32_16x16x32_bf16 v[28:31], v[152:155], v[188:191], v[28:31]
	v_mfma_f32_16x16x32_bf16 v[20:23], v[144:147], v[196:199], v[20:23]
	v_mfma_f32_16x16x32_bf16 v[12:15], v[152:155], v[196:199], v[12:15]
	v_mfma_f32_16x16x32_bf16 v[4:7], v[144:147], v[204:207], v[4:7]
	v_mfma_f32_16x16x32_bf16 v[0:3], v[152:155], v[204:207], v[0:3]
	v_mfma_f32_16x16x32_bf16 v[52:55], v[148:151], v[184:187], v[52:55]
	v_mfma_f32_16x16x32_bf16 v[44:47], v[156:159], v[184:187], v[44:47]
	v_mfma_f32_16x16x32_bf16 v[36:39], v[148:151], v[192:195], v[36:39]
	v_mfma_f32_16x16x32_bf16 v[28:31], v[156:159], v[192:195], v[28:31]
	v_mfma_f32_16x16x32_bf16 v[20:23], v[148:151], v[200:203], v[20:23]
	v_mfma_f32_16x16x32_bf16 v[12:15], v[156:159], v[200:203], v[12:15]
	v_mfma_f32_16x16x32_bf16 v[4:7], v[148:151], v[208:211], v[4:7]
	v_mfma_f32_16x16x32_bf16 v[0:3], v[156:159], v[208:211], v[0:3]
	s_setprio 0
	s_barrier
	s_add_i32 s51, s51, 2
	s_cmp_gt_u32 s51, 13
	s_cbranch_scc1 .LBB0_726
	s_mov_b64 s[20:21], s[22:23]
	s_branch .LBB0_721

.LBB0_1247:
	s_ashr_i32 s17, s16, 31
	s_lshl_b64 s[20:21], s[16:17], 18
	s_add_u32 s20, s88, s20
	s_addc_u32 s21, s89, s21
	s_and_b64 s[24:25], s[18:19], exec
	s_cselect_b32 s17, s21, s23
	s_cselect_b32 s50, s20, s22
	s_lshl_b32 s51, s46, 8
	s_or_b32 s52, s51, 0x80
	s_add_u32 s53, s22, 0x100
	s_addc_u32 s56, s23, 0
	s_mov_b32 s57, -2
	s_mov_b64 s[22:23], 0
	s_and_b64 vcc, exec, s[18:19]
	s_cbranch_vccz .Lgu_noidx
	s_add_i32 s54, s51, 64
	s_add_i32 s55, s52, 64
	v_add_lshl_u32 v248, v247, s51, 2
	v_add_lshl_u32 v249, v247, s54, 2
	v_add_lshl_u32 v250, v247, s52, 2
	v_add_lshl_u32 v251, v247, s55, 2
	global_load_dword v248, v248, s[0:1]
	global_load_dword v249, v249, s[0:1]
	global_load_dword v250, v250, s[0:1]
	global_load_dword v251, v251, s[0:1]
.Lgu_noidx:
	ds_read_b128 v[16:19], v177
	ds_read_b128 v[20:23], v177 offset:1024
	ds_read_b128 v[24:27], v177 offset:2048
	ds_read_b128 v[28:31], v177 offset:3072
	ds_read_b128 v[0:3], v178
	ds_read_b128 v[4:7], v178 offset:1024
	ds_read_b128 v[8:11], v178 offset:2048
	ds_read_b128 v[12:15], v178 offset:3072
	s_cmp_eq_u32 s57, 4
	s_cselect_b64 s[26:27], -1, 0
	s_add_u32 s24, s40, s22
	s_addc_u32 s25, s41, s23
	s_mov_b32 m0, s43
	ds_read_b128 v[180:183], v179
	ds_read_b128 v[184:187], v179 offset:1024
	ds_read_b128 v[188:191], v179 offset:2048
	ds_read_b128 v[192:195], v179 offset:3072
	ds_read_b128 v[196:199], v179 offset:4096
	ds_read_b128 v[200:203], v179 offset:5120
	ds_read_b128 v[204:207], v179 offset:6144
	ds_read_b128 v[208:211], v179 offset:7168
	global_load_lds_dwordx4 v168, s[24:25]
	s_mov_b32 m0, s44
	s_nop 0
	global_load_lds_dwordx4 v166, s[24:25]
	s_waitcnt vmcnt(8)
	s_waitcnt lgkmcnt(0)
	s_barrier
	s_setprio 1
	s_waitcnt lgkmcnt(0)
	v_mfma_f32_16x16x128_f8f6f4 v[156:159], v[16:23], v[180:187], 0
	v_mfma_f32_16x16x128_f8f6f4 v[152:155], v[24:31], v[180:187], 0
	v_mfma_f32_16x16x128_f8f6f4 v[140:143], v[16:23], v[188:195], 0
	v_mfma_f32_16x16x128_f8f6f4 v[136:139], v[24:31], v[188:195], 0
	v_mfma_f32_16x16x128_f8f6f4 v[124:127], v[16:23], v[196:203], 0
	v_mfma_f32_16x16x128_f8f6f4 v[120:123], v[24:31], v[196:203], 0
	v_mfma_f32_16x16x128_f8f6f4 v[108:111], v[16:23], v[204:211], 0
	v_mfma_f32_16x16x128_f8f6f4 v[104:107], v[24:31], v[204:211], 0
	v_mfma_f32_16x16x128_f8f6f4 v[148:151], v[0:7], v[180:187], 0
	v_mfma_f32_16x16x128_f8f6f4 v[144:147], v[8:15], v[180:187], 0
	v_mfma_f32_16x16x128_f8f6f4 v[132:135], v[0:7], v[188:195], 0
	v_mfma_f32_16x16x128_f8f6f4 v[128:131], v[8:15], v[188:195], 0
	v_mfma_f32_16x16x128_f8f6f4 v[116:119], v[0:7], v[196:203], 0
	v_mfma_f32_16x16x128_f8f6f4 v[112:115], v[8:15], v[196:203], 0
	v_mfma_f32_16x16x128_f8f6f4 v[100:103], v[0:7], v[204:211], 0
	v_mfma_f32_16x16x128_f8f6f4 v[96:99], v[8:15], v[204:211], 0
	s_setprio 0
	s_barrier
	s_and_b64 s[24:25], s[18:19], s[26:27]
	s_andn2_b64 vcc, exec, s[24:25]
	s_cbranch_vccnz .Lpk2_LBB0_1250
	v_lshl_add_u32 v164, v248, 10, v252
	v_lshl_add_u32 v170, v249, 10, v252
	v_lshl_add_u32 v168, v250, 10, v252
	v_lshl_add_u32 v166, v251, 10, v252
	v_mov_b32_e32 v167, v165
	v_mov_b32_e32 v172, v168
	v_mov_b32_e32 v173, v165
	s_branch .Lpk2_LBB0_1251

.Lpk2_LBB0_1251:
	s_add_u32 s24, s22, 0x100
	s_addc_u32 s25, s23, 0
	s_and_b64 s[70:71], s[26:27], exec
	s_cselect_b32 s6, 0, s24
	s_add_u32 s70, s53, s22
	s_addc_u32 s71, s56, s23
	s_and_b64 s[22:23], s[26:27], exec
	s_cselect_b32 s23, s17, s71
	s_cselect_b32 s22, s50, s70
	s_mov_b32 m0, s29
	v_lshl_add_u64 v[232:233], s[22:23], 0, v[162:163]
	s_add_u32 s26, s22, 0x20000
	ds_read_b128 v[180:183], v179 offset:16384
	ds_read_b128 v[184:187], v179 offset:17408
	ds_read_b128 v[188:191], v179 offset:18432
	ds_read_b128 v[192:195], v179 offset:19456
	ds_read_b128 v[196:199], v179 offset:20480
	ds_read_b128 v[200:203], v179 offset:21504
	ds_read_b128 v[204:207], v179 offset:22528
	ds_read_b128 v[208:211], v179 offset:23552
	global_load_lds_dwordx4 v[232:233], off
	v_lshl_add_u64 v[234:235], s[22:23], 0, v[160:161]
	s_mov_b32 m0, s30
	s_addc_u32 s27, s23, 0
	global_load_lds_dwordx4 v[234:235], off
	v_lshl_add_u64 v[212:213], s[26:27], 0, v[162:163]
	s_mov_b32 m0, s31
	v_mov_b32_e32 v171, v165
	global_load_lds_dwordx4 v[212:213], off
	v_lshl_add_u64 v[212:213], s[26:27], 0, v[160:161]
	s_mov_b32 m0, s34
	s_nop 0
	global_load_lds_dwordx4 v[212:213], off
	v_lshl_add_u64 v[212:213], s[4:5], 0, v[164:165]
	v_lshl_add_u64 v[236:237], v[212:213], 0, s[6:7]
	s_mov_b32 m0, s28
	v_lshl_add_u64 v[212:213], s[4:5], 0, v[170:171]
	global_load_lds_dwordx4 v[236:237], off
	v_lshl_add_u64 v[238:239], v[212:213], 0, s[6:7]
	s_mov_b32 m0, s35
	s_nop 0
	global_load_lds_dwordx4 v[238:239], off
	s_waitcnt vmcnt(8)
	s_waitcnt lgkmcnt(0)
	s_barrier
	s_setprio 1
	s_waitcnt lgkmcnt(0)
	v_mfma_f32_16x16x128_f8f6f4 v[92:95], v[16:23], v[180:187], 0
	v_mfma_f32_16x16x128_f8f6f4 v[88:91], v[24:31], v[180:187], 0
	v_mfma_f32_16x16x128_f8f6f4 v[76:79], v[16:23], v[188:195], 0
	v_mfma_f32_16x16x128_f8f6f4 v[72:75], v[24:31], v[188:195], 0
	v_mfma_f32_16x16x128_f8f6f4 v[212:215], v[16:23], v[196:203], 0
	v_mfma_f32_16x16x128_f8f6f4 v[216:219], v[24:31], v[196:203], 0
	v_mfma_f32_16x16x128_f8f6f4 v[220:223], v[16:23], v[204:211], 0
	v_mfma_f32_16x16x128_f8f6f4 v[224:227], v[24:31], v[204:211], 0
	v_mfma_f32_16x16x128_f8f6f4 v[84:87], v[0:7], v[180:187], 0
	v_mfma_f32_16x16x128_f8f6f4 v[80:83], v[8:15], v[180:187], 0
	v_mfma_f32_16x16x128_f8f6f4 v[68:71], v[0:7], v[188:195], 0
	v_mfma_f32_16x16x128_f8f6f4 v[64:67], v[8:15], v[188:195], 0
	v_mfma_f32_16x16x128_f8f6f4 v[228:231], v[0:7], v[196:203], 0
	v_mfma_f32_16x16x128_f8f6f4 v[196:199], v[8:15], v[196:203], 0
	v_mfma_f32_16x16x128_f8f6f4 v[200:203], v[0:7], v[204:211], 0
	v_mfma_f32_16x16x128_f8f6f4 v[204:207], v[8:15], v[204:211], 0
	s_setprio 0
	s_barrier
	s_add_i32 s26, 0, 0x18000
	s_add_i32 s27, 0, 0x1c000
	v_add_u32_e32 v12, s26, v176
	v_add_u32_e32 v28, s27, v176
	ds_read_b128 v[0:3], v12
	ds_read_b128 v[4:7], v12 offset:1024
	ds_read_b128 v[8:11], v12 offset:2048
	ds_read_b128 v[12:15], v12 offset:3072
	ds_read_b128 v[16:19], v28
	ds_read_b128 v[20:23], v28 offset:1024
	ds_read_b128 v[24:27], v28 offset:2048
	ds_read_b128 v[28:31], v28 offset:3072
	v_lshl_add_u64 v[172:173], s[4:5], 0, v[172:173]
	s_mov_b32 m0, s36
	v_lshl_add_u64 v[172:173], v[172:173], 0, s[6:7]
	ds_read_b128 v[32:35], v179 offset:32768
	ds_read_b128 v[36:39], v179 offset:33792
	ds_read_b128 v[40:43], v179 offset:34816
	ds_read_b128 v[44:47], v179 offset:35840
	ds_read_b128 v[48:51], v179 offset:36864
	ds_read_b128 v[52:55], v179 offset:37888
	ds_read_b128 v[56:59], v179 offset:38912
	ds_read_b128 v[60:63], v179 offset:39936
	global_load_lds_dwordx4 v[172:173], off
	v_lshl_add_u64 v[172:173], s[4:5], 0, v[166:167]
	v_lshl_add_u64 v[172:173], v[172:173], 0, s[6:7]
	s_mov_b32 m0, s37
	s_nop 0
	global_load_lds_dwordx4 v[172:173], off
	s_waitcnt vmcnt(8)
	s_waitcnt lgkmcnt(0)
	s_barrier
	s_setprio 1
	s_waitcnt lgkmcnt(0)
	v_mfma_f32_16x16x128_f8f6f4 v[156:159], v[0:7], v[32:39], v[156:159]
	v_mfma_f32_16x16x128_f8f6f4 v[152:155], v[8:15], v[32:39], v[152:155]
	v_mfma_f32_16x16x128_f8f6f4 v[140:143], v[0:7], v[40:47], v[140:143]
	v_mfma_f32_16x16x128_f8f6f4 v[136:139], v[8:15], v[40:47], v[136:139]
	v_mfma_f32_16x16x128_f8f6f4 v[124:127], v[0:7], v[48:55], v[124:127]
	v_mfma_f32_16x16x128_f8f6f4 v[120:123], v[8:15], v[48:55], v[120:123]
	v_mfma_f32_16x16x128_f8f6f4 v[108:111], v[0:7], v[56:63], v[108:111]
	v_mfma_f32_16x16x128_f8f6f4 v[104:107], v[8:15], v[56:63], v[104:107]
	v_mfma_f32_16x16x128_f8f6f4 v[148:151], v[16:23], v[32:39], v[148:151]
	v_mfma_f32_16x16x128_f8f6f4 v[144:147], v[24:31], v[32:39], v[144:147]
	v_mfma_f32_16x16x128_f8f6f4 v[132:135], v[16:23], v[40:47], v[132:135]
	v_mfma_f32_16x16x128_f8f6f4 v[128:131], v[24:31], v[40:47], v[128:131]
	v_mfma_f32_16x16x128_f8f6f4 v[116:119], v[16:23], v[48:55], v[116:119]
	v_mfma_f32_16x16x128_f8f6f4 v[112:115], v[24:31], v[48:55], v[112:115]
	v_mfma_f32_16x16x128_f8f6f4 v[100:103], v[16:23], v[56:63], v[100:103]
	v_mfma_f32_16x16x128_f8f6f4 v[96:99], v[24:31], v[56:63], v[96:99]
	s_setprio 0
	s_barrier
	s_add_i32 s6, s26, s84
	v_lshl_add_u64 v[40:41], v[232:233], 0, s[10:11]
	s_mov_b32 m0, s6
	ds_read_b128 v[32:35], v179 offset:49152
	ds_read_b128 v[36:39], v179 offset:50176
	ds_read_b128 v[48:51], v179 offset:51200
	ds_read_b128 v[52:55], v179 offset:52224
	ds_read_b128 v[180:183], v179 offset:53248
	ds_read_b128 v[184:187], v179 offset:54272
	ds_read_b128 v[188:191], v179 offset:55296
	ds_read_b128 v[192:195], v179 offset:56320
	global_load_lds_dwordx4 v[40:41], off
	s_add_i32 m0, s6, 0x2000
	s_add_u32 s22, s22, 0x20080
	v_lshl_add_u64 v[40:41], v[234:235], 0, s[10:11]
	s_addc_u32 s23, s23, 0
	s_add_i32 s6, s27, s84
	global_load_lds_dwordx4 v[40:41], off
	v_lshl_add_u64 v[40:41], s[22:23], 0, v[162:163]
	s_mov_b32 m0, s6
	s_nop 0
	global_load_lds_dwordx4 v[40:41], off
	v_lshl_add_u64 v[40:41], s[22:23], 0, v[160:161]
	s_add_i32 m0, s6, 0x2000
	s_nop 0
	global_load_lds_dwordx4 v[40:41], off
	v_lshl_add_u64 v[40:41], v[236:237], 0, s[10:11]
	s_mov_b32 m0, s38
	s_nop 0
	global_load_lds_dwordx4 v[40:41], off
	v_lshl_add_u64 v[40:41], v[238:239], 0, s[10:11]
	s_mov_b32 m0, s39
	s_nop 0
	global_load_lds_dwordx4 v[40:41], off
	s_waitcnt vmcnt(8)
	s_waitcnt lgkmcnt(0)
	s_barrier
	s_setprio 1
	s_waitcnt lgkmcnt(0)
	v_mfma_f32_16x16x128_f8f6f4 v[92:95], v[0:7], v[32:39], v[92:95]
	v_mfma_f32_16x16x128_f8f6f4 v[88:91], v[8:15], v[32:39], v[88:91]
	v_mfma_f32_16x16x128_f8f6f4 v[76:79], v[0:7], v[48:55], v[76:79]
	v_mfma_f32_16x16x128_f8f6f4 v[72:75], v[8:15], v[48:55], v[72:75]
	v_mfma_f32_16x16x128_f8f6f4 v[60:63], v[0:7], v[180:187], v[212:215]
	v_mfma_f32_16x16x128_f8f6f4 v[56:59], v[8:15], v[180:187], v[216:219]
	v_mfma_f32_16x16x128_f8f6f4 v[44:47], v[0:7], v[188:195], v[220:223]
	v_mfma_f32_16x16x128_f8f6f4 v[40:43], v[8:15], v[188:195], v[224:227]
	v_mfma_f32_16x16x128_f8f6f4 v[84:87], v[16:23], v[32:39], v[84:87]
	v_mfma_f32_16x16x128_f8f6f4 v[80:83], v[24:31], v[32:39], v[80:83]
	v_mfma_f32_16x16x128_f8f6f4 v[68:71], v[16:23], v[48:55], v[68:71]
	v_mfma_f32_16x16x128_f8f6f4 v[64:67], v[24:31], v[48:55], v[64:67]
	v_mfma_f32_16x16x128_f8f6f4 v[52:55], v[16:23], v[180:187], v[228:231]
	v_mfma_f32_16x16x128_f8f6f4 v[48:51], v[24:31], v[180:187], v[196:199]
	v_mfma_f32_16x16x128_f8f6f4 v[36:39], v[16:23], v[188:195], v[200:203]
	v_mfma_f32_16x16x128_f8f6f4 v[32:35], v[24:31], v[188:195], v[204:207]
	s_setprio 0
	s_barrier
	s_add_i32 s57, s57, 2
	s_cmp_gt_u32 s57, 5
	s_cbranch_scc1 .LBB0_1253
	s_mov_b64 s[22:23], s[24:25]
	s_branch .LBB0_1248

.LBB0_1323:
	s_lshl_b32 s48, s43, 8
	s_or_b32 s49, s48, 0x80
	s_add_u32 s50, s18, 0x100
	s_addc_u32 s51, s19, 0
	s_mov_b32 s52, -2
	s_mov_b64 s[18:19], 0
	ds_read_b128 v[16:19], v175
	ds_read_b128 v[20:23], v175 offset:1024
	ds_read_b128 v[24:27], v175 offset:2048
	ds_read_b128 v[28:31], v175 offset:3072
	ds_read_b128 v[0:3], v176
	ds_read_b128 v[4:7], v176 offset:1024
	ds_read_b128 v[8:11], v176 offset:2048
	ds_read_b128 v[12:15], v176 offset:3072
	s_cmp_eq_u32 s52, 18
	s_cselect_b64 s[22:23], -1, 0
	s_add_u32 s20, s38, s18
	s_addc_u32 s21, s39, s19
	s_mov_b32 m0, s40
	ds_read_b128 v[178:181], v177
	ds_read_b128 v[182:185], v177 offset:1024
	ds_read_b128 v[186:189], v177 offset:2048
	ds_read_b128 v[190:193], v177 offset:3072
	ds_read_b128 v[194:197], v177 offset:4096
	ds_read_b128 v[198:201], v177 offset:5120
	ds_read_b128 v[202:205], v177 offset:6144
	ds_read_b128 v[206:209], v177 offset:7168
	global_load_lds_dwordx4 v166, s[20:21]
	s_mov_b32 m0, s41
	s_nop 0
	global_load_lds_dwordx4 v170, s[20:21]
	s_waitcnt vmcnt(8)
	s_waitcnt lgkmcnt(0)
	s_barrier
	s_setprio 1
	s_waitcnt lgkmcnt(0)
	v_mfma_f32_16x16x128_f8f6f4 v[156:159], v[16:23], v[178:185], 0
	v_mfma_f32_16x16x128_f8f6f4 v[152:155], v[24:31], v[178:185], 0
	v_mfma_f32_16x16x128_f8f6f4 v[140:143], v[16:23], v[186:193], 0
	v_mfma_f32_16x16x128_f8f6f4 v[136:139], v[24:31], v[186:193], 0
	v_mfma_f32_16x16x128_f8f6f4 v[124:127], v[16:23], v[194:201], 0
	v_mfma_f32_16x16x128_f8f6f4 v[120:123], v[24:31], v[194:201], 0
	v_mfma_f32_16x16x128_f8f6f4 v[108:111], v[16:23], v[202:209], 0
	v_mfma_f32_16x16x128_f8f6f4 v[104:107], v[24:31], v[202:209], 0
	v_mfma_f32_16x16x128_f8f6f4 v[148:151], v[0:7], v[178:185], 0
	v_mfma_f32_16x16x128_f8f6f4 v[144:147], v[8:15], v[178:185], 0
	v_mfma_f32_16x16x128_f8f6f4 v[132:135], v[0:7], v[186:193], 0
	v_mfma_f32_16x16x128_f8f6f4 v[128:131], v[8:15], v[186:193], 0
	v_mfma_f32_16x16x128_f8f6f4 v[116:119], v[0:7], v[194:201], 0
	v_mfma_f32_16x16x128_f8f6f4 v[112:115], v[8:15], v[194:201], 0
	v_mfma_f32_16x16x128_f8f6f4 v[100:103], v[0:7], v[202:209], 0
	v_mfma_f32_16x16x128_f8f6f4 v[96:99], v[8:15], v[202:209], 0
	s_setprio 0
	s_barrier
	s_and_b64 s[20:21], s[16:17], s[22:23]
	s_andn2_b64 vcc, exec, s[20:21]
	s_cbranch_vccnz .Lpk3_LBB0_1326
	s_mul_i32 s57, s48, s28
	s_mul_i32 s58, s49, s28
	v_add_u32_e32 v164, s57, v247
	v_add_u32_e32 v166, s58, v247
	v_add_u32_e32 v168, 0x2c000, v164
	v_add_u32_e32 v170, 0x2c000, v166
	v_mov_b32_e32 v167, v165
	v_mov_b32_e32 v171, v165
	v_mov_b32_e32 v169, v165
	s_branch .Lpk3_LBB0_1327

.Lpk3_LBB0_1327:
	s_add_u32 s20, s18, 0x100
	s_addc_u32 s21, s19, 0
	s_and_b64 s[56:57], s[22:23], exec
	s_cselect_b32 s4, 0, s20
	s_add_u32 s53, s50, s18
	s_addc_u32 s56, s51, s19
	s_and_b64 s[18:19], s[22:23], exec
	s_cselect_b32 s19, s15, s56
	s_cselect_b32 s18, s14, s53
	s_mov_b32 m0, s26
	v_lshl_add_u64 v[230:231], s[18:19], 0, v[162:163]
	s_add_u32 s22, s18, 0x58000
	ds_read_b128 v[178:181], v177 offset:16384
	ds_read_b128 v[182:185], v177 offset:17408
	ds_read_b128 v[186:189], v177 offset:18432
	ds_read_b128 v[190:193], v177 offset:19456
	ds_read_b128 v[194:197], v177 offset:20480
	ds_read_b128 v[198:201], v177 offset:21504
	ds_read_b128 v[202:205], v177 offset:22528
	ds_read_b128 v[206:209], v177 offset:23552
	global_load_lds_dwordx4 v[230:231], off
	v_lshl_add_u64 v[232:233], s[18:19], 0, v[160:161]
	s_mov_b32 m0, s27
	s_addc_u32 s23, s19, 0
	global_load_lds_dwordx4 v[232:233], off
	v_lshl_add_u64 v[210:211], s[22:23], 0, v[162:163]
	s_mov_b32 m0, s29
	v_mov_b32_e32 v169, v165
	global_load_lds_dwordx4 v[210:211], off
	v_lshl_add_u64 v[210:211], s[22:23], 0, v[160:161]
	s_mov_b32 m0, s30
	s_nop 0
	global_load_lds_dwordx4 v[210:211], off
	v_lshl_add_u64 v[210:211], s[2:3], 0, v[164:165]
	v_lshl_add_u64 v[234:235], v[210:211], 0, s[4:5]
	s_mov_b32 m0, s25
	v_lshl_add_u64 v[210:211], s[2:3], 0, v[168:169]
	global_load_lds_dwordx4 v[234:235], off
	v_lshl_add_u64 v[236:237], v[210:211], 0, s[4:5]
	s_mov_b32 m0, s31
	s_nop 0
	global_load_lds_dwordx4 v[236:237], off
	s_waitcnt vmcnt(8)
	s_waitcnt lgkmcnt(0)
	s_barrier
	s_setprio 1
	s_waitcnt lgkmcnt(0)
	v_mfma_f32_16x16x128_f8f6f4 v[92:95], v[16:23], v[178:185], 0
	v_mfma_f32_16x16x128_f8f6f4 v[88:91], v[24:31], v[178:185], 0
	v_mfma_f32_16x16x128_f8f6f4 v[76:79], v[16:23], v[186:193], 0
	v_mfma_f32_16x16x128_f8f6f4 v[72:75], v[24:31], v[186:193], 0
	v_mfma_f32_16x16x128_f8f6f4 v[210:213], v[16:23], v[194:201], 0
	v_mfma_f32_16x16x128_f8f6f4 v[214:217], v[24:31], v[194:201], 0
	v_mfma_f32_16x16x128_f8f6f4 v[218:221], v[16:23], v[202:209], 0
	v_mfma_f32_16x16x128_f8f6f4 v[222:225], v[24:31], v[202:209], 0
	v_mfma_f32_16x16x128_f8f6f4 v[84:87], v[0:7], v[178:185], 0
	v_mfma_f32_16x16x128_f8f6f4 v[80:83], v[8:15], v[178:185], 0
	v_mfma_f32_16x16x128_f8f6f4 v[68:71], v[0:7], v[186:193], 0
	v_mfma_f32_16x16x128_f8f6f4 v[64:67], v[8:15], v[186:193], 0
	v_mfma_f32_16x16x128_f8f6f4 v[226:229], v[0:7], v[194:201], 0
	v_mfma_f32_16x16x128_f8f6f4 v[194:197], v[8:15], v[194:201], 0
	v_mfma_f32_16x16x128_f8f6f4 v[198:201], v[0:7], v[202:209], 0
	v_mfma_f32_16x16x128_f8f6f4 v[202:205], v[8:15], v[202:209], 0
	s_setprio 0
	s_barrier
	s_add_i32 s22, 0, 0x18000
	s_add_i32 s23, 0, 0x1c000
	v_add_u32_e32 v12, s22, v173
	v_add_u32_e32 v28, s23, v173
	ds_read_b128 v[0:3], v12
	ds_read_b128 v[4:7], v12 offset:1024
	ds_read_b128 v[8:11], v12 offset:2048
	ds_read_b128 v[12:15], v12 offset:3072
	ds_read_b128 v[16:19], v28
	ds_read_b128 v[20:23], v28 offset:1024
	ds_read_b128 v[24:27], v28 offset:2048
	ds_read_b128 v[28:31], v28 offset:3072
	v_lshl_add_u64 v[178:179], s[2:3], 0, v[166:167]
	s_mov_b32 m0, s34
	v_lshl_add_u64 v[178:179], v[178:179], 0, s[4:5]
	ds_read_b128 v[32:35], v177 offset:32768
	ds_read_b128 v[36:39], v177 offset:33792
	ds_read_b128 v[40:43], v177 offset:34816
	ds_read_b128 v[44:47], v177 offset:35840
	ds_read_b128 v[48:51], v177 offset:36864
	ds_read_b128 v[52:55], v177 offset:37888
	ds_read_b128 v[56:59], v177 offset:38912
	ds_read_b128 v[60:63], v177 offset:39936
	global_load_lds_dwordx4 v[178:179], off
	v_lshl_add_u64 v[178:179], s[2:3], 0, v[170:171]
	v_lshl_add_u64 v[178:179], v[178:179], 0, s[4:5]
	s_mov_b32 m0, s35
	s_nop 0
	global_load_lds_dwordx4 v[178:179], off
	s_waitcnt vmcnt(8)
	s_waitcnt lgkmcnt(0)
	s_barrier
	s_setprio 1
	s_waitcnt lgkmcnt(0)
	v_mfma_f32_16x16x128_f8f6f4 v[156:159], v[0:7], v[32:39], v[156:159]
	v_mfma_f32_16x16x128_f8f6f4 v[152:155], v[8:15], v[32:39], v[152:155]
	v_mfma_f32_16x16x128_f8f6f4 v[140:143], v[0:7], v[40:47], v[140:143]
	v_mfma_f32_16x16x128_f8f6f4 v[136:139], v[8:15], v[40:47], v[136:139]
	v_mfma_f32_16x16x128_f8f6f4 v[124:127], v[0:7], v[48:55], v[124:127]
	v_mfma_f32_16x16x128_f8f6f4 v[120:123], v[8:15], v[48:55], v[120:123]
	v_mfma_f32_16x16x128_f8f6f4 v[108:111], v[0:7], v[56:63], v[108:111]
	v_mfma_f32_16x16x128_f8f6f4 v[104:107], v[8:15], v[56:63], v[104:107]
	v_mfma_f32_16x16x128_f8f6f4 v[148:151], v[16:23], v[32:39], v[148:151]
	v_mfma_f32_16x16x128_f8f6f4 v[144:147], v[24:31], v[32:39], v[144:147]
	v_mfma_f32_16x16x128_f8f6f4 v[132:135], v[16:23], v[40:47], v[132:135]
	v_mfma_f32_16x16x128_f8f6f4 v[128:131], v[24:31], v[40:47], v[128:131]
	v_mfma_f32_16x16x128_f8f6f4 v[116:119], v[16:23], v[48:55], v[116:119]
	v_mfma_f32_16x16x128_f8f6f4 v[112:115], v[24:31], v[48:55], v[112:115]
	v_mfma_f32_16x16x128_f8f6f4 v[100:103], v[16:23], v[56:63], v[100:103]
	v_mfma_f32_16x16x128_f8f6f4 v[96:99], v[24:31], v[56:63], v[96:99]
	s_setprio 0
	s_barrier
	s_add_i32 s4, s22, s84
	v_lshl_add_u64 v[40:41], v[230:231], 0, s[10:11]
	s_mov_b32 m0, s4
	ds_read_b128 v[32:35], v177 offset:49152
	ds_read_b128 v[36:39], v177 offset:50176
	ds_read_b128 v[48:51], v177 offset:51200
	ds_read_b128 v[52:55], v177 offset:52224
	ds_read_b128 v[178:181], v177 offset:53248
	ds_read_b128 v[182:185], v177 offset:54272
	ds_read_b128 v[186:189], v177 offset:55296
	ds_read_b128 v[190:193], v177 offset:56320
	global_load_lds_dwordx4 v[40:41], off
	s_add_i32 m0, s4, 0x2000
	s_add_u32 s18, s18, 0x58080
	v_lshl_add_u64 v[40:41], v[232:233], 0, s[10:11]
	s_addc_u32 s19, s19, 0
	s_add_i32 s4, s23, s84
	global_load_lds_dwordx4 v[40:41], off
	v_lshl_add_u64 v[40:41], s[18:19], 0, v[162:163]
	s_mov_b32 m0, s4
	s_nop 0
	global_load_lds_dwordx4 v[40:41], off
	v_lshl_add_u64 v[40:41], s[18:19], 0, v[160:161]
	s_add_i32 m0, s4, 0x2000
	s_nop 0
	global_load_lds_dwordx4 v[40:41], off
	v_lshl_add_u64 v[40:41], v[234:235], 0, s[10:11]
	s_mov_b32 m0, s36
	s_nop 0
	global_load_lds_dwordx4 v[40:41], off
	v_lshl_add_u64 v[40:41], v[236:237], 0, s[10:11]
	s_mov_b32 m0, s37
	s_nop 0
	global_load_lds_dwordx4 v[40:41], off
	s_waitcnt vmcnt(8)
	s_waitcnt lgkmcnt(0)
	s_barrier
	s_setprio 1
	s_waitcnt lgkmcnt(0)
	v_mfma_f32_16x16x128_f8f6f4 v[92:95], v[0:7], v[32:39], v[92:95]
	v_mfma_f32_16x16x128_f8f6f4 v[88:91], v[8:15], v[32:39], v[88:91]
	v_mfma_f32_16x16x128_f8f6f4 v[76:79], v[0:7], v[48:55], v[76:79]
	v_mfma_f32_16x16x128_f8f6f4 v[72:75], v[8:15], v[48:55], v[72:75]
	v_mfma_f32_16x16x128_f8f6f4 v[60:63], v[0:7], v[178:185], v[210:213]
	v_mfma_f32_16x16x128_f8f6f4 v[56:59], v[8:15], v[178:185], v[214:217]
	v_mfma_f32_16x16x128_f8f6f4 v[44:47], v[0:7], v[186:193], v[218:221]
	v_mfma_f32_16x16x128_f8f6f4 v[40:43], v[8:15], v[186:193], v[222:225]
	v_mfma_f32_16x16x128_f8f6f4 v[84:87], v[16:23], v[32:39], v[84:87]
	v_mfma_f32_16x16x128_f8f6f4 v[80:83], v[24:31], v[32:39], v[80:83]
	v_mfma_f32_16x16x128_f8f6f4 v[68:71], v[16:23], v[48:55], v[68:71]
	v_mfma_f32_16x16x128_f8f6f4 v[64:67], v[24:31], v[48:55], v[64:67]
	v_mfma_f32_16x16x128_f8f6f4 v[52:55], v[16:23], v[178:185], v[226:229]
	v_mfma_f32_16x16x128_f8f6f4 v[48:51], v[24:31], v[178:185], v[194:197]
	v_mfma_f32_16x16x128_f8f6f4 v[36:39], v[16:23], v[186:193], v[198:201]
	v_mfma_f32_16x16x128_f8f6f4 v[32:35], v[24:31], v[186:193], v[202:205]
	s_setprio 0
	s_barrier
	s_add_i32 s52, s52, 2
	s_cmp_gt_u32 s52, 19
	s_cbranch_scc1 .LBB0_1329
	s_mov_b64 s[18:19], s[20:21]
	s_branch .LBB0_1324
